# EpiResid: per-unit epilogue parameter vectors staged once per workgroup in LDS (3 dword loads per thread + barrier) instead of 20 redundant dwordx4 global loads per wave
# baseline (speedup 1.0000x reference)
;     __device__ __forceinline__ void operator()(const f32x4 (&acc)[2][2][4][2], const pg8::Unit& u, int wr, int wc, int fr, int fq) const {
;     ...
;         const int row0 = rowt + wr * 64 + fr, col0 = u.pn * 256 + wc * 32 + 8 * fq;
;         const float* gp = gate + (size_t)grp * (NMOD * DM) + col0;
;         float sq[2][4];
; #pragma unroll
;         for (int ai = 0; ai < 2; ++ai)
; #pragma unroll
;             for (int m = 0; m < 4; ++m) sq[ai][m] = 0.f;
; #pragma unroll
;         for (int bj = 0; bj < 2; ++bj) {
;             const f32x4 g0 = *(const f32x4*)(gp + bj * 128) * coef, g1 = *(const f32x4*)(gp + bj * 128 + 4) * coef;
;             f32x4 s0, s1, i0, i1;
;             { const float* np_ = ngn + col0 + bj * 128; const float* sp_ = scn + (size_t)grp * (NMOD * DM) + col0 + bj * 128;
;                 s0 = *(const f32x4*)np_ * (*(const f32x4*)sp_ + 1.f); s1 = *(const f32x4*)(np_ + 4) * (*(const f32x4*)(sp_ + 4) + 1.f);
;                 const float* pp_ = ngp + col0 + bj * 128; const float* qp_ = scp + (size_t)grp * (NMOD * DM) + col0 + bj * 128;
;                 const f32x4 p0 = *(const f32x4*)pp_ * (*(const f32x4*)qp_ + 1.f), p1 = *(const f32x4*)(pp_ + 4) * (*(const f32x4*)(qp_ + 4) + 1.f);
;                 i0 = (f32x4){rcpf_(p0[0]), rcpf_(p0[1]), rcpf_(p0[2]), rcpf_(p0[3])}; i1 = (f32x4){rcpf_(p1[0]), rcpf_(p1[1]), rcpf_(p1[2]), rcpf_(p1[3])}; }
; #pragma unroll
;             for (int ai = 0; ai < 2; ++ai) {
;                 u32x4 rr[4];
; #pragma unroll
;                 for (int m = 0; m < 4; ++m) rr[m] = *(const u32x4*)(Un + (size_t)(row0 + ai * 128 + m * 16) * DM + col0 + bj * 128);
;                 __builtin_amdgcn_sched_barrier(0);
; #pragma unroll
;                 for (int m = 0; m < 4; ++m) {
;                     const size_t off = (size_t)(row0 + ai * 128 + m * 16) * DM + col0 + bj * 128;
;                     const u32x4 r = rr[m];
;                     f32x4 h0 = (f32x4){bf2f(r.x & 0xffffu), __builtin_bit_cast(float, r.x & 0xffff0000u), bf2f(r.y & 0xffffu), __builtin_bit_cast(float, r.y & 0xffff0000u)};
;                     f32x4 h1 = (f32x4){bf2f(r.z & 0xffffu), __builtin_bit_cast(float, r.z & 0xffff0000u), bf2f(r.w & 0xffffu), __builtin_bit_cast(float, r.w & 0xffff0000u)};
;                     h0 = h0 * i0 + g0 * acc[ai][bj][m][0]; h1 = h1 * i1 + g1 * acc[ai][bj][m][1];
.LBB0_316:
	s_ashr_i32 s1, s66, 6
	s_lshl_b32 s24, s46, 8
	s_or_b32 s33, s24, s48
	s_add_i32 s58, s17, s47
	s_mul_hi_i32 s25, s1, 0x9000
	s_mul_i32 s1, s1, 0x9000
	s_add_u32 s26, s49, s1
	s_addc_u32 s27, s50, s25
	s_add_u32 s66, s45, s1
	s_addc_u32 s67, s44, s25
	s_add_u32 s24, s51, s1
	s_addc_u32 s25, s52, s25
	v_readlane_b32 s0, v253, 48
	v_readlane_b32 s1, v253, 49
	s_waitcnt lgkmcnt(0)
	v_lshl_add_u32 v143, v235, 3, s33
	v_add_u32_e32 v163, s58, v234
	v_lshlrev_b32_e32 v154, 2, v143
	v_lshlrev_b32_e32 v222, 1, v143
	v_lshl_add_u32 v155, v163, 11, v222
	v_add_u32_e32 v156, 0x8000, v155
	v_add_u32_e32 v157, 0x10000, v155
	v_add_u32_e32 v158, 0x18000, v155
	v_add_u32_e32 v159, 0x40000, v155
	v_add_u32_e32 v160, 0x48000, v155
	v_add_u32_e32 v161, 0x50000, v155
	v_add_u32_e32 v162, 0x58000, v155
	v_mbcnt_lo_u32_b32 v228, -1, 0
	v_mbcnt_hi_u32_b32 v228, -1, v228
	s_lshl_b32 s33, s48, 1
	v_add_u32_e32 v228, s33, v228
	s_lshl_b32 s33, s46, 8
	v_add_lshl_u32 v229, v228, s33, 2
	v_lshlrev_b32_e32 v228, 2, v228
	s_cmp_eq_u32 s47, 0
	s_cselect_b32 s98, s26, s6
	s_cselect_b32 s99, s27, s7
	s_cselect_b32 s100, s66, s10
	s_cselect_b32 s101, s67, s11
	s_cselect_b32 s33, 0, 0x400
	global_load_dword v172, v229, s[98:99]
	global_load_dword v173, v229, s[100:101]
	global_load_dword v174, v229, s[24:25]
	v_add_u32_e32 v228, 0x20000, v228
	v_add_u32_e32 v229, s33, v228
	global_load_dwordx4 v[212:215], v155, s[0:1]
	global_load_dwordx4 v[216:219], v156, s[0:1]
	global_load_dwordx4 v[236:239], v157, s[0:1]
	global_load_dwordx4 v[240:243], v158, s[0:1]
	global_load_dwordx4 v[244:247], v159, s[0:1]
	global_load_dwordx4 v[248:251], v160, s[0:1]
	global_load_dwordx4 v[128:131], v161, s[0:1]
	global_load_dwordx4 v[132:135], v162, s[0:1]
	s_waitcnt vmcnt(8)
	ds_write_b32 v229, v172
	ds_write_b32 v229, v173 offset:2048
	ds_write_b32 v228, v174 offset:4096
	v_lshl_add_u32 v154, v235, 3, s48
	v_lshlrev_b32_e32 v154, 2, v154
	v_add_u32_e32 v154, 0x20000, v154
	s_waitcnt lgkmcnt(0)
	s_barrier
	ds_read_b128 v[172:175], v154 offset:0
	ds_read_b128 v[176:179], v154 offset:16
	ds_read_b128 v[180:183], v154 offset:1024
	ds_read_b128 v[184:187], v154 offset:1040
	ds_read_b128 v[188:191], v154 offset:2048
	ds_read_b128 v[192:195], v154 offset:2064
	ds_read_b128 v[196:199], v154 offset:3072
	ds_read_b128 v[200:203], v154 offset:3088
	ds_read_b128 v[204:207], v154 offset:4096
	ds_read_b128 v[208:211], v154 offset:4112
	s_waitcnt lgkmcnt(0)
	v_pk_mul_f32 v[172:173], v[148:149], v[172:173]
	v_pk_mul_f32 v[174:175], v[148:149], v[174:175]
	v_pk_mul_f32 v[176:177], v[148:149], v[176:177]
	v_pk_mul_f32 v[178:179], v[148:149], v[178:179]
	v_pk_add_f32 v[188:189], v[188:189], 1.0 op_sel_hi:[1,0]
	v_pk_add_f32 v[190:191], v[190:191], 1.0 op_sel_hi:[1,0]
	v_pk_add_f32 v[192:193], v[192:193], 1.0 op_sel_hi:[1,0]
	v_pk_add_f32 v[194:195], v[194:195], 1.0 op_sel_hi:[1,0]
	v_pk_add_f32 v[204:205], v[204:205], 1.0 op_sel_hi:[1,0]
	v_pk_add_f32 v[206:207], v[206:207], 1.0 op_sel_hi:[1,0]
	v_pk_add_f32 v[208:209], v[208:209], 1.0 op_sel_hi:[1,0]
	v_pk_add_f32 v[210:211], v[210:211], 1.0 op_sel_hi:[1,0]
	v_pk_mul_f32 v[180:181], v[180:181], v[188:189]
	v_pk_mul_f32 v[182:183], v[182:183], v[190:191]
	v_pk_mul_f32 v[184:185], v[184:185], v[192:193]
	v_pk_mul_f32 v[186:187], v[186:187], v[194:195]
	v_pk_mul_f32 v[196:197], v[196:197], v[204:205]
	v_pk_mul_f32 v[198:199], v[198:199], v[206:207]
	v_pk_mul_f32 v[200:201], v[200:201], v[208:209]
	v_pk_mul_f32 v[202:203], v[202:203], v[210:211]
	v_rcp_f32_e32 v196, v196
	v_rcp_f32_e32 v197, v197
	v_rcp_f32_e32 v198, v198
	v_rcp_f32_e32 v199, v199
	v_rcp_f32_e32 v200, v200
	v_rcp_f32_e32 v201, v201
	v_rcp_f32_e32 v202, v202
	v_rcp_f32_e32 v203, v203
	s_nop 0
	s_waitcnt vmcnt(4)
	v_lshlrev_b32_e32 v188, 16, v212
	v_and_b32_e32 v189, 0xffff0000, v212
	v_lshlrev_b32_e32 v190, 16, v213
	v_and_b32_e32 v191, 0xffff0000, v213
	v_lshlrev_b32_e32 v192, 16, v214
	v_and_b32_e32 v193, 0xffff0000, v214
	v_lshlrev_b32_e32 v194, 16, v215
	v_and_b32_e32 v195, 0xffff0000, v215
	v_pk_mul_f32 v[188:189], v[196:197], v[188:189]
	v_pk_mul_f32 v[190:191], v[198:199], v[190:191]
	v_pk_mul_f32 v[192:193], v[200:201], v[192:193]
	v_pk_mul_f32 v[194:195], v[202:203], v[194:195]
	v_pk_fma_f32 v[188:189], v[124:125], v[172:173], v[188:189]
	v_pk_fma_f32 v[190:191], v[126:127], v[174:175], v[190:191]
	v_pk_fma_f32 v[192:193], v[120:121], v[176:177], v[192:193]
	v_pk_fma_f32 v[194:195], v[122:123], v[178:179], v[194:195]
	v_mul_f32_e32 v222, v189, v189
	v_mul_f32_e32 v223, v191, v191
	v_fmac_f32_e32 v222, v188, v188
	v_fmac_f32_e32 v223, v190, v190
	v_add_f32_e32 v222, v222, v223
	v_mul_f32_e32 v223, v193, v193
	v_mul_f32_e32 v228, v195, v195
	v_fmac_f32_e32 v223, v192, v192
	v_fmac_f32_e32 v228, v194, v194
	v_add_f32_e32 v223, v223, v228
	v_add_f32_e32 v164, v222, v223
	v_pk_mul_f32 v[188:189], v[180:181], v[188:189]
	v_pk_mul_f32 v[190:191], v[182:183], v[190:191]
	v_pk_mul_f32 v[192:193], v[184:185], v[192:193]
	v_pk_mul_f32 v[194:195], v[186:187], v[194:195]
	v_cvt_pk_bf16_f32 v212, v188, v189
	v_cvt_pk_bf16_f32 v213, v190, v191
	v_cvt_pk_bf16_f32 v214, v192, v193
	v_cvt_pk_bf16_f32 v215, v194, v195
	global_store_dwordx4 v155, v[212:215], s[0:1]
	v_lshlrev_b32_e32 v188, 16, v216
	v_and_b32_e32 v189, 0xffff0000, v216
	v_lshlrev_b32_e32 v190, 16, v217
	v_and_b32_e32 v191, 0xffff0000, v217
	v_lshlrev_b32_e32 v192, 16, v218
	v_and_b32_e32 v193, 0xffff0000, v218
	v_lshlrev_b32_e32 v194, 16, v219
	v_and_b32_e32 v195, 0xffff0000, v219
	v_pk_mul_f32 v[188:189], v[196:197], v[188:189]
	v_pk_mul_f32 v[190:191], v[198:199], v[190:191]
	v_pk_mul_f32 v[192:193], v[200:201], v[192:193]
;     __device__ __forceinline__ void operator()(const f32x4 (&acc)[2][2][4][2], const pg8::Unit& u, int wr, int wc, int fr, int fq) const {
;     ...
;             const f32x4 g0 = *(const f32x4*)(gp + bj * 128) * coef, g1 = *(const f32x4*)(gp + bj * 128 + 4) * coef;
;             f32x4 s0, s1, i0, i1;
;             { const float* np_ = ngn + col0 + bj * 128; const float* sp_ = scn + (size_t)grp * (NMOD * DM) + col0 + bj * 128;
;                 s0 = *(const f32x4*)np_ * (*(const f32x4*)sp_ + 1.f); s1 = *(const f32x4*)(np_ + 4) * (*(const f32x4*)(sp_ + 4) + 1.f);
;                 const float* pp_ = ngp + col0 + bj * 128; const float* qp_ = scp + (size_t)grp * (NMOD * DM) + col0 + bj * 128;
;                 const f32x4 p0 = *(const f32x4*)pp_ * (*(const f32x4*)qp_ + 1.f), p1 = *(const f32x4*)(pp_ + 4) * (*(const f32x4*)(qp_ + 4) + 1.f);
;                 i0 = (f32x4){rcpf_(p0[0]), rcpf_(p0[1]), rcpf_(p0[2]), rcpf_(p0[3])}; i1 = (f32x4){rcpf_(p1[0]), rcpf_(p1[1]), rcpf_(p1[2]), rcpf_(p1[3])}; }
; #pragma unroll
;             for (int ai = 0; ai < 2; ++ai) {
;                 u32x4 rr[4];
; #pragma unroll
;                 for (int m = 0; m < 4; ++m) rr[m] = *(const u32x4*)(Un + (size_t)(row0 + ai * 128 + m * 16) * DM + col0 + bj * 128);
;                 __builtin_amdgcn_sched_barrier(0);
; #pragma unroll
;                 for (int m = 0; m < 4; ++m) {
;                     const size_t off = (size_t)(row0 + ai * 128 + m * 16) * DM + col0 + bj * 128;
;                     const u32x4 r = rr[m];
;                     f32x4 h0 = (f32x4){bf2f(r.x & 0xffffu), __builtin_bit_cast(float, r.x & 0xffff0000u), bf2f(r.y & 0xffffu), __builtin_bit_cast(float, r.y & 0xffff0000u)};
;                     f32x4 h1 = (f32x4){bf2f(r.z & 0xffffu), __builtin_bit_cast(float, r.z & 0xffff0000u), bf2f(r.w & 0xffffu), __builtin_bit_cast(float, r.w & 0xffff0000u)};
;                     h0 = h0 * i0 + g0 * acc[ai][bj][m][0]; h1 = h1 * i1 + g1 * acc[ai][bj][m][1];
;                     sq[ai][m] += ((h0[0] * h0[0] + h0[1] * h0[1]) + (h0[2] * h0[2] + h0[3] * h0[3])) + ((h1[0] * h1[0] + h1[1] * h1[1]) + (h1[2] * h1[2] + h1[3] * h1[3]));
;                     asm volatile("" : "+v"(sq[ai][m]));
;                     const f32x4 u0 = h0 * s0, u1 = h1 * s1;
;                     u32x4 w; w.x = pk2(u0[0], u0[1]); w.y = pk2(u0[2], u0[3]); w.z = pk2(u1[0], u1[1]); w.w = pk2(u1[2], u1[3]);
	v_pk_mul_f32 v[194:195], v[202:203], v[194:195]
	v_pk_fma_f32 v[188:189], v[116:117], v[172:173], v[188:189]
	v_pk_fma_f32 v[190:191], v[118:119], v[174:175], v[190:191]
	v_pk_fma_f32 v[192:193], v[112:113], v[176:177], v[192:193]
	v_pk_fma_f32 v[194:195], v[114:115], v[178:179], v[194:195]
	v_mul_f32_e32 v222, v189, v189
	v_mul_f32_e32 v223, v191, v191
	v_fmac_f32_e32 v222, v188, v188
	v_fmac_f32_e32 v223, v190, v190
	v_add_f32_e32 v222, v222, v223
	v_mul_f32_e32 v223, v193, v193
	v_mul_f32_e32 v228, v195, v195
	v_fmac_f32_e32 v223, v192, v192
	v_fmac_f32_e32 v228, v194, v194
	v_add_f32_e32 v223, v223, v228
	v_add_f32_e32 v165, v222, v223
	v_pk_mul_f32 v[188:189], v[180:181], v[188:189]
	v_pk_mul_f32 v[190:191], v[182:183], v[190:191]
	v_pk_mul_f32 v[192:193], v[184:185], v[192:193]
	v_pk_mul_f32 v[194:195], v[186:187], v[194:195]
	v_cvt_pk_bf16_f32 v216, v188, v189
	v_cvt_pk_bf16_f32 v217, v190, v191
	v_cvt_pk_bf16_f32 v218, v192, v193
	v_cvt_pk_bf16_f32 v219, v194, v195
	global_store_dwordx4 v156, v[216:219], s[0:1]
	v_lshlrev_b32_e32 v188, 16, v236
	v_and_b32_e32 v189, 0xffff0000, v236
	v_lshlrev_b32_e32 v190, 16, v237
	v_and_b32_e32 v191, 0xffff0000, v237
	v_lshlrev_b32_e32 v192, 16, v238
	v_and_b32_e32 v193, 0xffff0000, v238
	v_lshlrev_b32_e32 v194, 16, v239
	v_and_b32_e32 v195, 0xffff0000, v239
	v_pk_mul_f32 v[188:189], v[196:197], v[188:189]
	v_pk_mul_f32 v[190:191], v[198:199], v[190:191]
	v_pk_mul_f32 v[192:193], v[200:201], v[192:193]
	v_pk_mul_f32 v[194:195], v[202:203], v[194:195]
	v_pk_fma_f32 v[188:189], v[108:109], v[172:173], v[188:189]
	v_pk_fma_f32 v[190:191], v[110:111], v[174:175], v[190:191]
	v_pk_fma_f32 v[192:193], v[104:105], v[176:177], v[192:193]
	v_pk_fma_f32 v[194:195], v[106:107], v[178:179], v[194:195]
	v_mul_f32_e32 v222, v189, v189
	v_mul_f32_e32 v223, v191, v191
	v_fmac_f32_e32 v222, v188, v188
	v_fmac_f32_e32 v223, v190, v190
	v_add_f32_e32 v222, v222, v223
	v_mul_f32_e32 v223, v193, v193
	v_mul_f32_e32 v228, v195, v195
	v_fmac_f32_e32 v223, v192, v192
	v_fmac_f32_e32 v228, v194, v194
	v_add_f32_e32 v223, v223, v228
	v_add_f32_e32 v166, v222, v223
	v_pk_mul_f32 v[188:189], v[180:181], v[188:189]
	v_pk_mul_f32 v[190:191], v[182:183], v[190:191]
	v_pk_mul_f32 v[192:193], v[184:185], v[192:193]
	v_pk_mul_f32 v[194:195], v[186:187], v[194:195]
	v_cvt_pk_bf16_f32 v236, v188, v189
	v_cvt_pk_bf16_f32 v237, v190, v191
	v_cvt_pk_bf16_f32 v238, v192, v193
	v_cvt_pk_bf16_f32 v239, v194, v195
	global_store_dwordx4 v157, v[236:239], s[0:1]
	v_lshlrev_b32_e32 v188, 16, v240
	v_and_b32_e32 v189, 0xffff0000, v240
	v_lshlrev_b32_e32 v190, 16, v241
	v_and_b32_e32 v191, 0xffff0000, v241
	v_lshlrev_b32_e32 v192, 16, v242
	v_and_b32_e32 v193, 0xffff0000, v242
	v_lshlrev_b32_e32 v194, 16, v243
	v_and_b32_e32 v195, 0xffff0000, v243
	v_pk_mul_f32 v[188:189], v[196:197], v[188:189]
	v_pk_mul_f32 v[190:191], v[198:199], v[190:191]
	v_pk_mul_f32 v[192:193], v[200:201], v[192:193]
	v_pk_mul_f32 v[194:195], v[202:203], v[194:195]
	v_pk_fma_f32 v[188:189], v[100:101], v[172:173], v[188:189]
	v_pk_fma_f32 v[190:191], v[102:103], v[174:175], v[190:191]
	v_pk_fma_f32 v[192:193], v[96:97], v[176:177], v[192:193]
	v_pk_fma_f32 v[194:195], v[98:99], v[178:179], v[194:195]
	v_mul_f32_e32 v222, v189, v189
	v_mul_f32_e32 v223, v191, v191
	v_fmac_f32_e32 v222, v188, v188
	v_fmac_f32_e32 v223, v190, v190
	v_add_f32_e32 v222, v222, v223
	v_mul_f32_e32 v223, v193, v193
	v_mul_f32_e32 v228, v195, v195
	v_fmac_f32_e32 v223, v192, v192
	v_fmac_f32_e32 v228, v194, v194
	v_add_f32_e32 v223, v223, v228
	v_add_f32_e32 v167, v222, v223
	v_pk_mul_f32 v[188:189], v[180:181], v[188:189]
	v_pk_mul_f32 v[190:191], v[182:183], v[190:191]
	v_pk_mul_f32 v[192:193], v[184:185], v[192:193]
	v_pk_mul_f32 v[194:195], v[186:187], v[194:195]
	v_cvt_pk_bf16_f32 v240, v188, v189
	v_cvt_pk_bf16_f32 v241, v190, v191
	v_cvt_pk_bf16_f32 v242, v192, v193
	v_cvt_pk_bf16_f32 v243, v194, v195
	global_store_dwordx4 v158, v[240:243], s[0:1]
	global_load_dwordx4 v[236:239], v155, s[0:1] offset:256
	global_load_dwordx4 v[240:243], v156, s[0:1] offset:256
	global_load_dwordx4 v[204:207], v157, s[0:1] offset:256
	global_load_dwordx4 v[208:211], v158, s[0:1] offset:256
	ds_read_b128 v[96:99], v154 offset:512
	ds_read_b128 v[100:103], v154 offset:528
	ds_read_b128 v[104:107], v154 offset:1536
	ds_read_b128 v[108:111], v154 offset:1552
	ds_read_b128 v[112:115], v154 offset:2560
	ds_read_b128 v[116:119], v154 offset:2576
	ds_read_b128 v[120:123], v154 offset:3584
	ds_read_b128 v[124:127], v154 offset:3600
	ds_read_b128 v[212:215], v154 offset:4608
	ds_read_b128 v[216:219], v154 offset:4624
	s_waitcnt vmcnt(8)
; __device__ __forceinline__ unsigned pk2(float lo, float hi) { unsigned r; asm("v_cvt_pk_bf16_f32 %0, %1, %2" : "=v"(r) : "v"(lo), "v"(hi)); return r; }
;     __device__ __forceinline__ void operator()(const f32x4 (&acc)[2][2][4][2], const pg8::Unit& u, int wr, int wc, int fr, int fq) const {
;     ...
;                 for (int m = 0; m < 4; ++m) rr[m] = *(const u32x4*)(Un + (size_t)(row0 + ai * 128 + m * 16) * DM + col0 + bj * 128);
;                 __builtin_amdgcn_sched_barrier(0);
; #pragma unroll
;                 for (int m = 0; m < 4; ++m) {
;                     const size_t off = (size_t)(row0 + ai * 128 + m * 16) * DM + col0 + bj * 128;
;                     const u32x4 r = rr[m];
;                     f32x4 h0 = (f32x4){bf2f(r.x & 0xffffu), __builtin_bit_cast(float, r.x & 0xffff0000u), bf2f(r.y & 0xffffu), __builtin_bit_cast(float, r.y & 0xffff0000u)};
;                     f32x4 h1 = (f32x4){bf2f(r.z & 0xffffu), __builtin_bit_cast(float, r.z & 0xffff0000u), bf2f(r.w & 0xffffu), __builtin_bit_cast(float, r.w & 0xffff0000u)};
;                     h0 = h0 * i0 + g0 * acc[ai][bj][m][0]; h1 = h1 * i1 + g1 * acc[ai][bj][m][1];
;                     sq[ai][m] += ((h0[0] * h0[0] + h0[1] * h0[1]) + (h0[2] * h0[2] + h0[3] * h0[3])) + ((h1[0] * h1[0] + h1[1] * h1[1]) + (h1[2] * h1[2] + h1[3] * h1[3]));
;                     asm volatile("" : "+v"(sq[ai][m]));
;                     const f32x4 u0 = h0 * s0, u1 = h1 * s1;
;                     u32x4 w; w.x = pk2(u0[0], u0[1]); w.y = pk2(u0[2], u0[3]); w.z = pk2(u1[0], u1[1]); w.w = pk2(u1[2], u1[3]);
;                     *(u32x4*)(Un + off) = w;
	v_lshlrev_b32_e32 v188, 16, v244
	v_and_b32_e32 v189, 0xffff0000, v244
	v_lshlrev_b32_e32 v190, 16, v245
	v_and_b32_e32 v191, 0xffff0000, v245
	v_lshlrev_b32_e32 v192, 16, v246
	v_and_b32_e32 v193, 0xffff0000, v246
	v_lshlrev_b32_e32 v194, 16, v247
	v_and_b32_e32 v195, 0xffff0000, v247
	v_pk_mul_f32 v[188:189], v[196:197], v[188:189]
	v_pk_mul_f32 v[190:191], v[198:199], v[190:191]
	v_pk_mul_f32 v[192:193], v[200:201], v[192:193]
	v_pk_mul_f32 v[194:195], v[202:203], v[194:195]
	v_pk_fma_f32 v[188:189], v[92:93], v[172:173], v[188:189]
	v_pk_fma_f32 v[190:191], v[94:95], v[174:175], v[190:191]
	v_pk_fma_f32 v[192:193], v[88:89], v[176:177], v[192:193]
	v_pk_fma_f32 v[194:195], v[90:91], v[178:179], v[194:195]
	v_mul_f32_e32 v222, v189, v189
	v_mul_f32_e32 v223, v191, v191
	v_fmac_f32_e32 v222, v188, v188
	v_fmac_f32_e32 v223, v190, v190
	v_add_f32_e32 v222, v222, v223
	v_mul_f32_e32 v223, v193, v193
	v_mul_f32_e32 v228, v195, v195
	v_fmac_f32_e32 v223, v192, v192
	v_fmac_f32_e32 v228, v194, v194
	v_add_f32_e32 v223, v223, v228
	v_add_f32_e32 v168, v222, v223
	v_pk_mul_f32 v[188:189], v[180:181], v[188:189]
	v_pk_mul_f32 v[190:191], v[182:183], v[190:191]
	v_pk_mul_f32 v[192:193], v[184:185], v[192:193]
	v_pk_mul_f32 v[194:195], v[186:187], v[194:195]
	v_cvt_pk_bf16_f32 v244, v188, v189
	v_cvt_pk_bf16_f32 v245, v190, v191
	v_cvt_pk_bf16_f32 v246, v192, v193
	v_cvt_pk_bf16_f32 v247, v194, v195
	global_store_dwordx4 v159, v[244:247], s[0:1]
	v_lshlrev_b32_e32 v188, 16, v248
	v_and_b32_e32 v189, 0xffff0000, v248
	v_lshlrev_b32_e32 v190, 16, v249
	v_and_b32_e32 v191, 0xffff0000, v249
	v_lshlrev_b32_e32 v192, 16, v250
	v_and_b32_e32 v193, 0xffff0000, v250
	v_lshlrev_b32_e32 v194, 16, v251
	v_and_b32_e32 v195, 0xffff0000, v251
	v_pk_mul_f32 v[188:189], v[196:197], v[188:189]
	v_pk_mul_f32 v[190:191], v[198:199], v[190:191]
	v_pk_mul_f32 v[192:193], v[200:201], v[192:193]
	v_pk_mul_f32 v[194:195], v[202:203], v[194:195]
	v_pk_fma_f32 v[188:189], v[84:85], v[172:173], v[188:189]
	v_pk_fma_f32 v[190:191], v[86:87], v[174:175], v[190:191]
	v_pk_fma_f32 v[192:193], v[80:81], v[176:177], v[192:193]
	v_pk_fma_f32 v[194:195], v[82:83], v[178:179], v[194:195]
	v_mul_f32_e32 v222, v189, v189
	v_mul_f32_e32 v223, v191, v191
	v_fmac_f32_e32 v222, v188, v188
	v_fmac_f32_e32 v223, v190, v190
	v_add_f32_e32 v222, v222, v223
	v_mul_f32_e32 v223, v193, v193
	v_mul_f32_e32 v228, v195, v195
	v_fmac_f32_e32 v223, v192, v192
	v_fmac_f32_e32 v228, v194, v194
	v_add_f32_e32 v223, v223, v228
	v_add_f32_e32 v169, v222, v223
	v_pk_mul_f32 v[188:189], v[180:181], v[188:189]
	v_pk_mul_f32 v[190:191], v[182:183], v[190:191]
	v_pk_mul_f32 v[192:193], v[184:185], v[192:193]
	v_pk_mul_f32 v[194:195], v[186:187], v[194:195]
	v_cvt_pk_bf16_f32 v248, v188, v189
	v_cvt_pk_bf16_f32 v249, v190, v191
	v_cvt_pk_bf16_f32 v250, v192, v193
	v_cvt_pk_bf16_f32 v251, v194, v195
	global_store_dwordx4 v160, v[248:251], s[0:1]
	v_lshlrev_b32_e32 v188, 16, v128
	v_and_b32_e32 v189, 0xffff0000, v128
	v_lshlrev_b32_e32 v190, 16, v129
	v_and_b32_e32 v191, 0xffff0000, v129
	v_lshlrev_b32_e32 v192, 16, v130
	v_and_b32_e32 v193, 0xffff0000, v130
	v_lshlrev_b32_e32 v194, 16, v131
	v_and_b32_e32 v195, 0xffff0000, v131
	v_pk_mul_f32 v[188:189], v[196:197], v[188:189]
	v_pk_mul_f32 v[190:191], v[198:199], v[190:191]
	v_pk_mul_f32 v[192:193], v[200:201], v[192:193]
	v_pk_mul_f32 v[194:195], v[202:203], v[194:195]
	v_pk_fma_f32 v[188:189], v[76:77], v[172:173], v[188:189]
	v_pk_fma_f32 v[190:191], v[78:79], v[174:175], v[190:191]
	v_pk_fma_f32 v[192:193], v[72:73], v[176:177], v[192:193]
	v_pk_fma_f32 v[194:195], v[74:75], v[178:179], v[194:195]
	v_mul_f32_e32 v222, v189, v189
	v_mul_f32_e32 v223, v191, v191
	v_fmac_f32_e32 v222, v188, v188
	v_fmac_f32_e32 v223, v190, v190
	v_add_f32_e32 v222, v222, v223
	v_mul_f32_e32 v223, v193, v193
	v_mul_f32_e32 v228, v195, v195
	v_fmac_f32_e32 v223, v192, v192
	v_fmac_f32_e32 v228, v194, v194
	v_add_f32_e32 v223, v223, v228
	v_add_f32_e32 v170, v222, v223
	v_pk_mul_f32 v[188:189], v[180:181], v[188:189]
	v_pk_mul_f32 v[190:191], v[182:183], v[190:191]
	v_pk_mul_f32 v[192:193], v[184:185], v[192:193]
	v_pk_mul_f32 v[194:195], v[186:187], v[194:195]
	v_cvt_pk_bf16_f32 v128, v188, v189
	v_cvt_pk_bf16_f32 v129, v190, v191
	v_cvt_pk_bf16_f32 v130, v192, v193
	v_cvt_pk_bf16_f32 v131, v194, v195
	global_store_dwordx4 v161, v[128:131], s[0:1]
	v_lshlrev_b32_e32 v188, 16, v132
	v_and_b32_e32 v189, 0xffff0000, v132
	v_lshlrev_b32_e32 v190, 16, v133
	v_and_b32_e32 v191, 0xffff0000, v133
	v_lshlrev_b32_e32 v192, 16, v134
	v_and_b32_e32 v193, 0xffff0000, v134
	v_lshlrev_b32_e32 v194, 16, v135
	v_and_b32_e32 v195, 0xffff0000, v135
	v_pk_mul_f32 v[188:189], v[196:197], v[188:189]
	v_pk_mul_f32 v[190:191], v[198:199], v[190:191]
	v_pk_mul_f32 v[192:193], v[200:201], v[192:193]
	v_pk_mul_f32 v[194:195], v[202:203], v[194:195]
	v_pk_fma_f32 v[188:189], v[68:69], v[172:173], v[188:189]
	v_pk_fma_f32 v[190:191], v[70:71], v[174:175], v[190:191]
	v_pk_fma_f32 v[192:193], v[64:65], v[176:177], v[192:193]
	v_pk_fma_f32 v[194:195], v[66:67], v[178:179], v[194:195]
	v_mul_f32_e32 v222, v189, v189
	v_mul_f32_e32 v223, v191, v191
	v_fmac_f32_e32 v222, v188, v188
	v_fmac_f32_e32 v223, v190, v190
	v_add_f32_e32 v222, v222, v223
	v_mul_f32_e32 v223, v193, v193
	v_mul_f32_e32 v228, v195, v195
	v_fmac_f32_e32 v223, v192, v192
	v_fmac_f32_e32 v228, v194, v194
	v_add_f32_e32 v223, v223, v228
	v_add_f32_e32 v171, v222, v223
	v_pk_mul_f32 v[188:189], v[180:181], v[188:189]
	v_pk_mul_f32 v[190:191], v[182:183], v[190:191]
	v_pk_mul_f32 v[192:193], v[184:185], v[192:193]
	v_pk_mul_f32 v[194:195], v[186:187], v[194:195]
	v_cvt_pk_bf16_f32 v132, v188, v189
	v_cvt_pk_bf16_f32 v133, v190, v191
	v_cvt_pk_bf16_f32 v134, v192, v193
	v_cvt_pk_bf16_f32 v135, v194, v195
	global_store_dwordx4 v162, v[132:135], s[0:1]
	s_nop 1
	global_load_dwordx4 v[244:247], v159, s[0:1] offset:256
	global_load_dwordx4 v[248:251], v160, s[0:1] offset:256
	global_load_dwordx4 v[128:131], v161, s[0:1] offset:256
	global_load_dwordx4 v[132:135], v162, s[0:1] offset:256
	s_waitcnt lgkmcnt(0)
;     __device__ __forceinline__ void operator()(const f32x4 (&acc)[2][2][4][2], const pg8::Unit& u, int wr, int wc, int fr, int fq) const {
;     ...
;             const f32x4 g0 = *(const f32x4*)(gp + bj * 128) * coef, g1 = *(const f32x4*)(gp + bj * 128 + 4) * coef;
;             f32x4 s0, s1, i0, i1;
;             { const float* np_ = ngn + col0 + bj * 128; const float* sp_ = scn + (size_t)grp * (NMOD * DM) + col0 + bj * 128;
;                 s0 = *(const f32x4*)np_ * (*(const f32x4*)sp_ + 1.f); s1 = *(const f32x4*)(np_ + 4) * (*(const f32x4*)(sp_ + 4) + 1.f);
;                 const float* pp_ = ngp + col0 + bj * 128; const float* qp_ = scp + (size_t)grp * (NMOD * DM) + col0 + bj * 128;
;                 const f32x4 p0 = *(const f32x4*)pp_ * (*(const f32x4*)qp_ + 1.f), p1 = *(const f32x4*)(pp_ + 4) * (*(const f32x4*)(qp_ + 4) + 1.f);
;                 i0 = (f32x4){rcpf_(p0[0]), rcpf_(p0[1]), rcpf_(p0[2]), rcpf_(p0[3])}; i1 = (f32x4){rcpf_(p1[0]), rcpf_(p1[1]), rcpf_(p1[2]), rcpf_(p1[3])}; }
; #pragma unroll
;             for (int ai = 0; ai < 2; ++ai) {
;                 u32x4 rr[4];
; #pragma unroll
;                 for (int m = 0; m < 4; ++m) rr[m] = *(const u32x4*)(Un + (size_t)(row0 + ai * 128 + m * 16) * DM + col0 + bj * 128);
;                 __builtin_amdgcn_sched_barrier(0);
; #pragma unroll
;                 for (int m = 0; m < 4; ++m) {
;                     const size_t off = (size_t)(row0 + ai * 128 + m * 16) * DM + col0 + bj * 128;
;                     const u32x4 r = rr[m];
;                     f32x4 h0 = (f32x4){bf2f(r.x & 0xffffu), __builtin_bit_cast(float, r.x & 0xffff0000u), bf2f(r.y & 0xffffu), __builtin_bit_cast(float, r.y & 0xffff0000u)};
;                     f32x4 h1 = (f32x4){bf2f(r.z & 0xffffu), __builtin_bit_cast(float, r.z & 0xffff0000u), bf2f(r.w & 0xffffu), __builtin_bit_cast(float, r.w & 0xffff0000u)};
;                     h0 = h0 * i0 + g0 * acc[ai][bj][m][0]; h1 = h1 * i1 + g1 * acc[ai][bj][m][1];
;                     sq[ai][m] += ((h0[0] * h0[0] + h0[1] * h0[1]) + (h0[2] * h0[2] + h0[3] * h0[3])) + ((h1[0] * h1[0] + h1[1] * h1[1]) + (h1[2] * h1[2] + h1[3] * h1[3]));
;                     asm volatile("" : "+v"(sq[ai][m]));
;                     const f32x4 u0 = h0 * s0, u1 = h1 * s1;
;                     u32x4 w; w.x = pk2(u0[0], u0[1]); w.y = pk2(u0[2], u0[3]); w.z = pk2(u1[0], u1[1]); w.w = pk2(u1[2], u1[3]);
	v_pk_mul_f32 v[96:97], v[148:149], v[96:97]
	v_pk_mul_f32 v[98:99], v[148:149], v[98:99]
	v_pk_mul_f32 v[100:101], v[148:149], v[100:101]
	v_pk_mul_f32 v[102:103], v[148:149], v[102:103]
	v_pk_add_f32 v[112:113], v[112:113], 1.0 op_sel_hi:[1,0]
	v_pk_add_f32 v[114:115], v[114:115], 1.0 op_sel_hi:[1,0]
	v_pk_add_f32 v[116:117], v[116:117], 1.0 op_sel_hi:[1,0]
	v_pk_add_f32 v[118:119], v[118:119], 1.0 op_sel_hi:[1,0]
	v_pk_add_f32 v[212:213], v[212:213], 1.0 op_sel_hi:[1,0]
	v_pk_add_f32 v[214:215], v[214:215], 1.0 op_sel_hi:[1,0]
	v_pk_add_f32 v[216:217], v[216:217], 1.0 op_sel_hi:[1,0]
	v_pk_add_f32 v[218:219], v[218:219], 1.0 op_sel_hi:[1,0]
	v_pk_mul_f32 v[104:105], v[104:105], v[112:113]
	v_pk_mul_f32 v[106:107], v[106:107], v[114:115]
	v_pk_mul_f32 v[108:109], v[108:109], v[116:117]
	v_pk_mul_f32 v[110:111], v[110:111], v[118:119]
	v_pk_mul_f32 v[120:121], v[120:121], v[212:213]
	v_pk_mul_f32 v[122:123], v[122:123], v[214:215]
	v_pk_mul_f32 v[124:125], v[124:125], v[216:217]
	v_pk_mul_f32 v[126:127], v[126:127], v[218:219]
	v_rcp_f32_e32 v120, v120
	v_rcp_f32_e32 v121, v121
	v_rcp_f32_e32 v122, v122
	v_rcp_f32_e32 v123, v123
	v_rcp_f32_e32 v124, v124
	v_rcp_f32_e32 v125, v125
	v_rcp_f32_e32 v126, v126
	v_rcp_f32_e32 v127, v127
	s_nop 0
	s_waitcnt vmcnt(8)
	v_lshlrev_b32_e32 v188, 16, v236
	v_and_b32_e32 v189, 0xffff0000, v236
	v_lshlrev_b32_e32 v190, 16, v237
	v_and_b32_e32 v191, 0xffff0000, v237
	v_lshlrev_b32_e32 v192, 16, v238
	v_and_b32_e32 v193, 0xffff0000, v238
	v_lshlrev_b32_e32 v194, 16, v239
	v_and_b32_e32 v195, 0xffff0000, v239
	v_pk_mul_f32 v[188:189], v[120:121], v[188:189]
	v_pk_mul_f32 v[190:191], v[122:123], v[190:191]
	v_pk_mul_f32 v[192:193], v[124:125], v[192:193]
	v_pk_mul_f32 v[194:195], v[126:127], v[194:195]
	v_pk_fma_f32 v[188:189], v[60:61], v[96:97], v[188:189]
	v_pk_fma_f32 v[190:191], v[62:63], v[98:99], v[190:191]
	v_pk_fma_f32 v[192:193], v[56:57], v[100:101], v[192:193]
	v_pk_fma_f32 v[194:195], v[58:59], v[102:103], v[194:195]
	v_mul_f32_e32 v222, v189, v189
	v_mul_f32_e32 v223, v191, v191
	v_fmac_f32_e32 v222, v188, v188
	v_fmac_f32_e32 v223, v190, v190
	v_add_f32_e32 v222, v222, v223
	v_mul_f32_e32 v223, v193, v193
	v_mul_f32_e32 v228, v195, v195
	v_fmac_f32_e32 v223, v192, v192
	v_fmac_f32_e32 v228, v194, v194
	v_add_f32_e32 v223, v223, v228
	v_add_f32_e32 v222, v222, v223
	v_add_f32_e32 v164, v164, v222
	v_pk_mul_f32 v[188:189], v[104:105], v[188:189]
	v_pk_mul_f32 v[190:191], v[106:107], v[190:191]
	v_pk_mul_f32 v[192:193], v[108:109], v[192:193]
	v_pk_mul_f32 v[194:195], v[110:111], v[194:195]
	v_cvt_pk_bf16_f32 v236, v188, v189
	v_cvt_pk_bf16_f32 v237, v190, v191
	v_cvt_pk_bf16_f32 v238, v192, v193
	v_cvt_pk_bf16_f32 v239, v194, v195
	global_store_dwordx4 v155, v[236:239], s[0:1] offset:256
	v_lshlrev_b32_e32 v188, 16, v240
	v_and_b32_e32 v189, 0xffff0000, v240
	v_lshlrev_b32_e32 v190, 16, v241
	v_and_b32_e32 v191, 0xffff0000, v241
	v_lshlrev_b32_e32 v192, 16, v242
	v_and_b32_e32 v193, 0xffff0000, v242
	v_lshlrev_b32_e32 v194, 16, v243
	v_and_b32_e32 v195, 0xffff0000, v243
	v_pk_mul_f32 v[188:189], v[120:121], v[188:189]
	v_pk_mul_f32 v[190:191], v[122:123], v[190:191]
	v_pk_mul_f32 v[192:193], v[124:125], v[192:193]
	v_pk_mul_f32 v[194:195], v[126:127], v[194:195]
	v_pk_fma_f32 v[188:189], v[52:53], v[96:97], v[188:189]
	v_pk_fma_f32 v[190:191], v[54:55], v[98:99], v[190:191]
	v_pk_fma_f32 v[192:193], v[48:49], v[100:101], v[192:193]
	v_pk_fma_f32 v[194:195], v[50:51], v[102:103], v[194:195]
	v_mul_f32_e32 v222, v189, v189
	v_mul_f32_e32 v223, v191, v191
	v_fmac_f32_e32 v222, v188, v188
	v_fmac_f32_e32 v223, v190, v190
	v_add_f32_e32 v222, v222, v223
	v_mul_f32_e32 v223, v193, v193
	v_mul_f32_e32 v228, v195, v195
	v_fmac_f32_e32 v223, v192, v192
	v_fmac_f32_e32 v228, v194, v194
	v_add_f32_e32 v223, v223, v228
	v_add_f32_e32 v222, v222, v223
	v_add_f32_e32 v165, v165, v222
	v_pk_mul_f32 v[188:189], v[104:105], v[188:189]
	v_pk_mul_f32 v[190:191], v[106:107], v[190:191]
	v_pk_mul_f32 v[192:193], v[108:109], v[192:193]
	v_pk_mul_f32 v[194:195], v[110:111], v[194:195]
	v_cvt_pk_bf16_f32 v240, v188, v189
	v_cvt_pk_bf16_f32 v241, v190, v191
	v_cvt_pk_bf16_f32 v242, v192, v193
	v_cvt_pk_bf16_f32 v243, v194, v195
	global_store_dwordx4 v156, v[240:243], s[0:1] offset:256
	v_lshlrev_b32_e32 v188, 16, v204
	v_and_b32_e32 v189, 0xffff0000, v204
	v_lshlrev_b32_e32 v190, 16, v205
	v_and_b32_e32 v191, 0xffff0000, v205
	v_lshlrev_b32_e32 v192, 16, v206
	v_and_b32_e32 v193, 0xffff0000, v206
	v_lshlrev_b32_e32 v194, 16, v207
	v_and_b32_e32 v195, 0xffff0000, v207
	v_pk_mul_f32 v[188:189], v[120:121], v[188:189]
	v_pk_mul_f32 v[190:191], v[122:123], v[190:191]
	v_pk_mul_f32 v[192:193], v[124:125], v[192:193]
	v_pk_mul_f32 v[194:195], v[126:127], v[194:195]
	v_pk_fma_f32 v[188:189], v[44:45], v[96:97], v[188:189]
	v_pk_fma_f32 v[190:191], v[46:47], v[98:99], v[190:191]
	v_pk_fma_f32 v[192:193], v[40:41], v[100:101], v[192:193]
	v_pk_fma_f32 v[194:195], v[42:43], v[102:103], v[194:195]
	v_mul_f32_e32 v222, v189, v189
	v_mul_f32_e32 v223, v191, v191
	v_fmac_f32_e32 v222, v188, v188
	v_fmac_f32_e32 v223, v190, v190
	v_add_f32_e32 v222, v222, v223
	v_mul_f32_e32 v223, v193, v193
	v_mul_f32_e32 v228, v195, v195
	v_fmac_f32_e32 v223, v192, v192
	v_fmac_f32_e32 v228, v194, v194
	v_add_f32_e32 v223, v223, v228
	v_add_f32_e32 v222, v222, v223
	v_add_f32_e32 v166, v166, v222
	v_pk_mul_f32 v[188:189], v[104:105], v[188:189]
	v_pk_mul_f32 v[190:191], v[106:107], v[190:191]
	v_pk_mul_f32 v[192:193], v[108:109], v[192:193]
	v_pk_mul_f32 v[194:195], v[110:111], v[194:195]
	v_cvt_pk_bf16_f32 v204, v188, v189
	v_cvt_pk_bf16_f32 v205, v190, v191
; __device__ __forceinline__ unsigned pk2(float lo, float hi) { unsigned r; asm("v_cvt_pk_bf16_f32 %0, %1, %2" : "=v"(r) : "v"(lo), "v"(hi)); return r; }
;     __device__ __forceinline__ void operator()(const f32x4 (&acc)[2][2][4][2], const pg8::Unit& u, int wr, int wc, int fr, int fq) const {
;     ...
;                 for (int m = 0; m < 4; ++m) {
;                     const size_t off = (size_t)(row0 + ai * 128 + m * 16) * DM + col0 + bj * 128;
;                     const u32x4 r = rr[m];
;                     f32x4 h0 = (f32x4){bf2f(r.x & 0xffffu), __builtin_bit_cast(float, r.x & 0xffff0000u), bf2f(r.y & 0xffffu), __builtin_bit_cast(float, r.y & 0xffff0000u)};
;                     f32x4 h1 = (f32x4){bf2f(r.z & 0xffffu), __builtin_bit_cast(float, r.z & 0xffff0000u), bf2f(r.w & 0xffffu), __builtin_bit_cast(float, r.w & 0xffff0000u)};
;                     h0 = h0 * i0 + g0 * acc[ai][bj][m][0]; h1 = h1 * i1 + g1 * acc[ai][bj][m][1];
;                     sq[ai][m] += ((h0[0] * h0[0] + h0[1] * h0[1]) + (h0[2] * h0[2] + h0[3] * h0[3])) + ((h1[0] * h1[0] + h1[1] * h1[1]) + (h1[2] * h1[2] + h1[3] * h1[3]));
;                     asm volatile("" : "+v"(sq[ai][m]));
;                     const f32x4 u0 = h0 * s0, u1 = h1 * s1;
;                     u32x4 w; w.x = pk2(u0[0], u0[1]); w.y = pk2(u0[2], u0[3]); w.z = pk2(u1[0], u1[1]); w.w = pk2(u1[2], u1[3]);
;                     *(u32x4*)(Un + off) = w;
	v_cvt_pk_bf16_f32 v206, v192, v193
	v_cvt_pk_bf16_f32 v207, v194, v195
	global_store_dwordx4 v157, v[204:207], s[0:1] offset:256
	v_lshlrev_b32_e32 v188, 16, v208
	v_and_b32_e32 v189, 0xffff0000, v208
	v_lshlrev_b32_e32 v190, 16, v209
	v_and_b32_e32 v191, 0xffff0000, v209
	v_lshlrev_b32_e32 v192, 16, v210
	v_and_b32_e32 v193, 0xffff0000, v210
	v_lshlrev_b32_e32 v194, 16, v211
	v_and_b32_e32 v195, 0xffff0000, v211
	v_pk_mul_f32 v[188:189], v[120:121], v[188:189]
	v_pk_mul_f32 v[190:191], v[122:123], v[190:191]
	v_pk_mul_f32 v[192:193], v[124:125], v[192:193]
	v_pk_mul_f32 v[194:195], v[126:127], v[194:195]
	v_pk_fma_f32 v[188:189], v[36:37], v[96:97], v[188:189]
	v_pk_fma_f32 v[190:191], v[38:39], v[98:99], v[190:191]
	v_pk_fma_f32 v[192:193], v[32:33], v[100:101], v[192:193]
	v_pk_fma_f32 v[194:195], v[34:35], v[102:103], v[194:195]
	v_mul_f32_e32 v222, v189, v189
	v_mul_f32_e32 v223, v191, v191
	v_fmac_f32_e32 v222, v188, v188
	v_fmac_f32_e32 v223, v190, v190
	v_add_f32_e32 v222, v222, v223
	v_mul_f32_e32 v223, v193, v193
	v_mul_f32_e32 v228, v195, v195
	v_fmac_f32_e32 v223, v192, v192
	v_fmac_f32_e32 v228, v194, v194
	v_add_f32_e32 v223, v223, v228
	v_add_f32_e32 v222, v222, v223
	v_add_f32_e32 v167, v167, v222
	v_pk_mul_f32 v[188:189], v[104:105], v[188:189]
	v_pk_mul_f32 v[190:191], v[106:107], v[190:191]
	v_pk_mul_f32 v[192:193], v[108:109], v[192:193]
	v_pk_mul_f32 v[194:195], v[110:111], v[194:195]
	v_cvt_pk_bf16_f32 v208, v188, v189
	v_cvt_pk_bf16_f32 v209, v190, v191
	v_cvt_pk_bf16_f32 v210, v192, v193
	v_cvt_pk_bf16_f32 v211, v194, v195
	global_store_dwordx4 v158, v[208:211], s[0:1] offset:256
	s_waitcnt vmcnt(4)
	v_lshlrev_b32_e32 v188, 16, v244
	v_and_b32_e32 v189, 0xffff0000, v244
	v_lshlrev_b32_e32 v190, 16, v245
	v_and_b32_e32 v191, 0xffff0000, v245
	v_lshlrev_b32_e32 v192, 16, v246
	v_and_b32_e32 v193, 0xffff0000, v246
	v_lshlrev_b32_e32 v194, 16, v247
	v_and_b32_e32 v195, 0xffff0000, v247
	v_pk_mul_f32 v[188:189], v[120:121], v[188:189]
	v_pk_mul_f32 v[190:191], v[122:123], v[190:191]
	v_pk_mul_f32 v[192:193], v[124:125], v[192:193]
	v_pk_mul_f32 v[194:195], v[126:127], v[194:195]
	v_pk_fma_f32 v[188:189], v[28:29], v[96:97], v[188:189]
	v_pk_fma_f32 v[190:191], v[30:31], v[98:99], v[190:191]
	v_pk_fma_f32 v[192:193], v[24:25], v[100:101], v[192:193]
	v_pk_fma_f32 v[194:195], v[26:27], v[102:103], v[194:195]
	v_mul_f32_e32 v222, v189, v189
	v_mul_f32_e32 v223, v191, v191
	v_fmac_f32_e32 v222, v188, v188
	v_fmac_f32_e32 v223, v190, v190
	v_add_f32_e32 v222, v222, v223
	v_mul_f32_e32 v223, v193, v193
	v_mul_f32_e32 v228, v195, v195
	v_fmac_f32_e32 v223, v192, v192
	v_fmac_f32_e32 v228, v194, v194
	v_add_f32_e32 v223, v223, v228
	v_add_f32_e32 v222, v222, v223
	v_add_f32_e32 v168, v168, v222
	v_pk_mul_f32 v[188:189], v[104:105], v[188:189]
	v_pk_mul_f32 v[190:191], v[106:107], v[190:191]
	v_pk_mul_f32 v[192:193], v[108:109], v[192:193]
	v_pk_mul_f32 v[194:195], v[110:111], v[194:195]
	v_cvt_pk_bf16_f32 v244, v188, v189
	v_cvt_pk_bf16_f32 v245, v190, v191
	v_cvt_pk_bf16_f32 v246, v192, v193
	v_cvt_pk_bf16_f32 v247, v194, v195
	global_store_dwordx4 v159, v[244:247], s[0:1] offset:256
	v_lshlrev_b32_e32 v188, 16, v248
	v_and_b32_e32 v189, 0xffff0000, v248
	v_lshlrev_b32_e32 v190, 16, v249
	v_and_b32_e32 v191, 0xffff0000, v249
	v_lshlrev_b32_e32 v192, 16, v250
	v_and_b32_e32 v193, 0xffff0000, v250
	v_lshlrev_b32_e32 v194, 16, v251
	v_and_b32_e32 v195, 0xffff0000, v251
	v_pk_mul_f32 v[188:189], v[120:121], v[188:189]
	v_pk_mul_f32 v[190:191], v[122:123], v[190:191]
	v_pk_mul_f32 v[192:193], v[124:125], v[192:193]
	v_pk_mul_f32 v[194:195], v[126:127], v[194:195]
	v_pk_fma_f32 v[188:189], v[20:21], v[96:97], v[188:189]
	v_pk_fma_f32 v[190:191], v[22:23], v[98:99], v[190:191]
	v_pk_fma_f32 v[192:193], v[16:17], v[100:101], v[192:193]
	v_pk_fma_f32 v[194:195], v[18:19], v[102:103], v[194:195]
	v_mul_f32_e32 v222, v189, v189
	v_mul_f32_e32 v223, v191, v191
	v_fmac_f32_e32 v222, v188, v188
	v_fmac_f32_e32 v223, v190, v190
	v_add_f32_e32 v222, v222, v223
	v_mul_f32_e32 v223, v193, v193
	v_mul_f32_e32 v228, v195, v195
	v_fmac_f32_e32 v223, v192, v192
	v_fmac_f32_e32 v228, v194, v194
	v_add_f32_e32 v223, v223, v228
	v_add_f32_e32 v222, v222, v223
	v_add_f32_e32 v169, v169, v222
	v_pk_mul_f32 v[188:189], v[104:105], v[188:189]
	v_pk_mul_f32 v[190:191], v[106:107], v[190:191]
	v_pk_mul_f32 v[192:193], v[108:109], v[192:193]
	v_pk_mul_f32 v[194:195], v[110:111], v[194:195]
	v_cvt_pk_bf16_f32 v248, v188, v189
	v_cvt_pk_bf16_f32 v249, v190, v191
	v_cvt_pk_bf16_f32 v250, v192, v193
	v_cvt_pk_bf16_f32 v251, v194, v195
	global_store_dwordx4 v160, v[248:251], s[0:1] offset:256
	v_lshlrev_b32_e32 v188, 16, v128
	v_and_b32_e32 v189, 0xffff0000, v128
	v_lshlrev_b32_e32 v190, 16, v129
	v_and_b32_e32 v191, 0xffff0000, v129
	v_lshlrev_b32_e32 v192, 16, v130
; __device__ __forceinline__ unsigned pk2(float lo, float hi) { unsigned r; asm("v_cvt_pk_bf16_f32 %0, %1, %2" : "=v"(r) : "v"(lo), "v"(hi)); return r; }
; __device__ __forceinline__ float shx(float v, int m, int lane) { return __builtin_bit_cast(float, __builtin_amdgcn_ds_bpermute((lane ^ m) << 2, __builtin_bit_cast(int, v))); }
;     __device__ __forceinline__ void operator()(const f32x4 (&acc)[2][2][4][2], const pg8::Unit& u, int wr, int wc, int fr, int fq) const {
;     ...
;                 for (int m = 0; m < 4; ++m) {
;                     const size_t off = (size_t)(row0 + ai * 128 + m * 16) * DM + col0 + bj * 128;
;                     const u32x4 r = rr[m];
;                     f32x4 h0 = (f32x4){bf2f(r.x & 0xffffu), __builtin_bit_cast(float, r.x & 0xffff0000u), bf2f(r.y & 0xffffu), __builtin_bit_cast(float, r.y & 0xffff0000u)};
;                     f32x4 h1 = (f32x4){bf2f(r.z & 0xffffu), __builtin_bit_cast(float, r.z & 0xffff0000u), bf2f(r.w & 0xffffu), __builtin_bit_cast(float, r.w & 0xffff0000u)};
;                     h0 = h0 * i0 + g0 * acc[ai][bj][m][0]; h1 = h1 * i1 + g1 * acc[ai][bj][m][1];
;                     sq[ai][m] += ((h0[0] * h0[0] + h0[1] * h0[1]) + (h0[2] * h0[2] + h0[3] * h0[3])) + ((h1[0] * h1[0] + h1[1] * h1[1]) + (h1[2] * h1[2] + h1[3] * h1[3]));
;                     asm volatile("" : "+v"(sq[ai][m]));
;                     const f32x4 u0 = h0 * s0, u1 = h1 * s1;
;                     u32x4 w; w.x = pk2(u0[0], u0[1]); w.y = pk2(u0[2], u0[3]); w.z = pk2(u1[0], u1[1]); w.w = pk2(u1[2], u1[3]);
;                     *(u32x4*)(Un + off) = w;
;                 }
;                 __builtin_amdgcn_sched_barrier(0);
;             }
;         }
;         if (Un) {
; #pragma unroll
;             for (int ai = 0; ai < 2; ++ai)
; #pragma unroll
;                 for (int m = 0; m < 4; ++m) { float t = sq[ai][m]; t += shx(t, 16, fq * 16 + fr); t += shx(t, 32, fq * 16 + fr);
;                     if (fq == 0) ssn[(size_t)(row0 + ai * 128 + m * 16) * 16 + u.pn * 4 + wc] = t; }
;         }
	v_and_b32_e32 v193, 0xffff0000, v130
	v_lshlrev_b32_e32 v194, 16, v131
	v_and_b32_e32 v195, 0xffff0000, v131
	v_pk_mul_f32 v[188:189], v[120:121], v[188:189]
	v_pk_mul_f32 v[190:191], v[122:123], v[190:191]
	v_pk_mul_f32 v[192:193], v[124:125], v[192:193]
	v_pk_mul_f32 v[194:195], v[126:127], v[194:195]
	v_pk_fma_f32 v[188:189], v[12:13], v[96:97], v[188:189]
	v_pk_fma_f32 v[190:191], v[14:15], v[98:99], v[190:191]
	v_pk_fma_f32 v[192:193], v[8:9], v[100:101], v[192:193]
	v_pk_fma_f32 v[194:195], v[10:11], v[102:103], v[194:195]
	v_mul_f32_e32 v222, v189, v189
	v_mul_f32_e32 v223, v191, v191
	v_fmac_f32_e32 v222, v188, v188
	v_fmac_f32_e32 v223, v190, v190
	v_add_f32_e32 v222, v222, v223
	v_mul_f32_e32 v223, v193, v193
	v_mul_f32_e32 v228, v195, v195
	v_fmac_f32_e32 v223, v192, v192
	v_fmac_f32_e32 v228, v194, v194
	v_add_f32_e32 v223, v223, v228
	v_add_f32_e32 v222, v222, v223
	v_add_f32_e32 v170, v170, v222
	v_pk_mul_f32 v[188:189], v[104:105], v[188:189]
	v_pk_mul_f32 v[190:191], v[106:107], v[190:191]
	v_pk_mul_f32 v[192:193], v[108:109], v[192:193]
	v_pk_mul_f32 v[194:195], v[110:111], v[194:195]
	v_cvt_pk_bf16_f32 v128, v188, v189
	v_cvt_pk_bf16_f32 v129, v190, v191
	v_cvt_pk_bf16_f32 v130, v192, v193
	v_cvt_pk_bf16_f32 v131, v194, v195
	global_store_dwordx4 v161, v[128:131], s[0:1] offset:256
	v_lshlrev_b32_e32 v188, 16, v132
	v_and_b32_e32 v189, 0xffff0000, v132
	v_lshlrev_b32_e32 v190, 16, v133
	v_and_b32_e32 v191, 0xffff0000, v133
	v_lshlrev_b32_e32 v192, 16, v134
	v_and_b32_e32 v193, 0xffff0000, v134
	v_lshlrev_b32_e32 v194, 16, v135
	v_and_b32_e32 v195, 0xffff0000, v135
	v_pk_mul_f32 v[188:189], v[120:121], v[188:189]
	v_pk_mul_f32 v[190:191], v[122:123], v[190:191]
	v_pk_mul_f32 v[192:193], v[124:125], v[192:193]
	v_pk_mul_f32 v[194:195], v[126:127], v[194:195]
	v_pk_fma_f32 v[188:189], v[4:5], v[96:97], v[188:189]
	v_pk_fma_f32 v[190:191], v[6:7], v[98:99], v[190:191]
	v_pk_fma_f32 v[192:193], v[0:1], v[100:101], v[192:193]
	v_pk_fma_f32 v[194:195], v[2:3], v[102:103], v[194:195]
	v_mul_f32_e32 v222, v189, v189
	v_mul_f32_e32 v223, v191, v191
	v_fmac_f32_e32 v222, v188, v188
	v_fmac_f32_e32 v223, v190, v190
	v_add_f32_e32 v222, v222, v223
	v_mul_f32_e32 v223, v193, v193
	v_mul_f32_e32 v228, v195, v195
	v_fmac_f32_e32 v223, v192, v192
	v_fmac_f32_e32 v228, v194, v194
	v_add_f32_e32 v223, v223, v228
	v_add_f32_e32 v222, v222, v223
	v_add_f32_e32 v171, v171, v222
	v_pk_mul_f32 v[188:189], v[104:105], v[188:189]
	v_pk_mul_f32 v[190:191], v[106:107], v[190:191]
	v_pk_mul_f32 v[192:193], v[108:109], v[192:193]
	v_pk_mul_f32 v[194:195], v[110:111], v[194:195]
	v_cvt_pk_bf16_f32 v132, v188, v189
	v_cvt_pk_bf16_f32 v133, v190, v191
	v_cvt_pk_bf16_f32 v134, v192, v193
	v_cvt_pk_bf16_f32 v135, v194, v195
	global_store_dwordx4 v162, v[132:135], s[0:1] offset:256
	v_lshlrev_b32_e32 v222, 2, v234
	v_lshl_add_u32 v223, v235, 6, v222
	v_xor_b32_e32 v222, 64, v223
	v_xor_b32_e32 v223, 0x80, v223
	ds_bpermute_b32 v188, v222, v164
	ds_bpermute_b32 v189, v222, v165
	ds_bpermute_b32 v190, v222, v166
	ds_bpermute_b32 v191, v222, v167
	ds_bpermute_b32 v192, v222, v168
	ds_bpermute_b32 v193, v222, v169
	ds_bpermute_b32 v194, v222, v170
	ds_bpermute_b32 v195, v222, v171
	s_lshl_b32 s24, s46, 4
	s_add_u32 s24, s57, s24
	s_addc_u32 s25, s59, 0
	v_lshlrev_b32_e32 v204, 6, v163
	v_add_u32_e32 v205, 0x400, v204
	v_add_u32_e32 v206, 0x800, v204
	v_add_u32_e32 v207, 0xc00, v204
	v_add_u32_e32 v208, 0x2000, v204
	v_add_u32_e32 v209, 0x2400, v204
	v_add_u32_e32 v210, 0x2800, v204
	v_add_u32_e32 v211, 0x2c00, v204
	s_waitcnt lgkmcnt(0)
	v_add_f32_e32 v164, v164, v188
	v_add_f32_e32 v165, v165, v189
	v_add_f32_e32 v166, v166, v190
	v_add_f32_e32 v167, v167, v191
	v_add_f32_e32 v168, v168, v192
	v_add_f32_e32 v169, v169, v193
	v_add_f32_e32 v170, v170, v194
	v_add_f32_e32 v171, v171, v195
	ds_bpermute_b32 v188, v223, v164
	ds_bpermute_b32 v189, v223, v165
	ds_bpermute_b32 v190, v223, v166
	ds_bpermute_b32 v191, v223, v167
	ds_bpermute_b32 v192, v223, v168
	ds_bpermute_b32 v193, v223, v169
	ds_bpermute_b32 v194, v223, v170
	ds_bpermute_b32 v195, v223, v171
	v_cmp_eq_u32_e32 vcc, 0, v235
	s_waitcnt lgkmcnt(0)
	v_add_f32_e32 v164, v164, v188
	v_add_f32_e32 v165, v165, v189
	v_add_f32_e32 v166, v166, v190
	v_add_f32_e32 v167, v167, v191
	v_add_f32_e32 v168, v168, v192
	v_add_f32_e32 v169, v169, v193
	v_add_f32_e32 v170, v170, v194
	v_add_f32_e32 v171, v171, v195
	s_and_saveexec_b64 s[26:27], vcc
	global_store_dword v204, v164, s[24:25]
	global_store_dword v205, v165, s[24:25]
	global_store_dword v206, v166, s[24:25]
	global_store_dword v207, v167, s[24:25]
	global_store_dword v208, v168, s[24:25]
	global_store_dword v209, v169, s[24:25]
	global_store_dword v210, v170, s[24:25]
	global_store_dword v211, v171, s[24:25]
	s_or_b64 exec, exec, s[26:27]
